# P1 weight-conversion items re-dealt: workgroups without an ada item take 4-5 items per wave, workgroups that ran an ada item first take one
# speedup vs baseline: 1.0135x; 1.0135x over previous
; #define LAS __attribute__((address_space(3)))
; __device__ __forceinline__ int opaque_tid() { int t = threadIdx.x; asm volatile("" : "+v"(t)); return t; }
; __device__ __forceinline__ void phase0(LAS unsigned char* lds, const Params& P) {
;     for (int item = blockIdx.x; item < 192; item += gridDim.x) p0_ada_item(lds, P, item);
; __device__ __forceinline__ void phase1(LAS unsigned char* lds, const Params& P) {
;     const int tid = opaque_tid(), lane = tid & 63, wid = __builtin_amdgcn_readfirstlane(tid >> 6);
;     const int G = gridDim.x;
;     const int gw = blockIdx.x * NWAVES + wid, NGW = G * NWAVES;
;     const float* ADA = (const float*)(P.ws + WS_ADA); bf16_t* HN = (bf16_t*)(P.ws + WS_HN);
;     LAS float* scr = (LAS float*)(lds + wid * 16384);
;     constexpr int I_IN = (DM / 64) * (DIN / 32), I_OUT = (2 * DM / 64) * (DM / 32), I_LRU = 32 * 8;
;     bf16_t* WinT = (bf16_t*)(P.ws + WS_WINT); bf16_t* WoutT = (bf16_t*)(P.ws + WS_WOUTT); bf16_t* LruW = (bf16_t*)(P.ws + WS_LRUW);
;     for (int it = gw; it < I_IN + I_OUT + I_LRU; it += NGW) {
;         int r = it;
;         if (r < I_IN) { p0_transpose_item<true>(P.w_in, DM, DIN, WinT, 1.0f, scr, r, lane); continue; } r -= I_IN;
;         if (r < I_OUT) { p0_transpose_item(P.w_out, 2 * DM, DM, WoutT, 1.0f, scr, r, lane); continue; } r -= I_OUT;
;         { const int mat = r >> 3, sub = r & 7, dir = mat >> 4, gate = (mat >> 3) & 1, h = mat & 7;
;           const float* src = (gate ? P.lru_wx : P.lru_wa) + (size_t)(dir * 8 + h) * 16384;
;           p0_transpose_item(src, 128, 128, LruW + (size_t)((dir * 2 + gate) * 8 + h) * 16384, -LOG2E, scr, sub, lane); }
;     }
.LBB0_33:
	s_waitcnt vmcnt(5)
	v_mov_b32_e32 v17, v167
	s_nop 0
	v_readfirstlane_b32 s79, v17
	s_ashr_i32 s0, s79, 6
	v_and_b32_e32 v162, 63, v17
	s_add_i32 s78, s0, s2
	s_cmpk_gt_i32 s78, 0xeff
	v_lshlrev_b32_e32 v16, 3, v162
	s_cbranch_scc1 .LBB0_52
	s_lshl_b32 s1, s0, 14
	v_lshrrev_b32_e32 v18, 5, v162
	v_and_b32_e32 v19, 31, v17
	s_add_i32 s1, s1, 0
	v_lshlrev_b32_e32 v4, 2, v19
	v_mul_u32_u24_e32 v0, 0x84, v18
	s_waitcnt vmcnt(4)
	v_lshrrev_b32_e32 v21, 3, v162
	v_and_b32_e32 v6, 56, v16
	v_add3_u32 v20, s1, v4, v0
	v_mul_u32_u24_e32 v0, 0x84, v6
	v_lshlrev_b32_e32 v1, 2, v21
	v_add3_u32 v22, s1, v0, v1
	s_bfe_u32 s1, s79, 0x30006
	s_lshl_b32 s44, s1, 5
	s_add_i32 s76, s44, 0xff80
	s_cmp_lt_u32 s1, 4
	s_cselect_b32 s1, s44, s76
	s_and_b32 s1, s1, 0xffe0
	v_or_b32_e32 v23, 8, v21
	v_or_b32_e32 v5, s1, v21
	v_or_b32_e32 v24, 16, v21
	v_lshlrev_b32_e32 v8, 7, v5
	v_or_b32_e32 v5, s1, v23
	v_or_b32_e32 v25, 24, v21
	v_lshlrev_b32_e32 v10, 7, v5
	v_or_b32_e32 v5, s1, v24
	v_lshlrev_b32_e32 v12, 7, v5
	v_or_b32_e32 v5, s1, v25
	v_lshlrev_b32_e32 v160, 1, v6
	v_lshlrev_b32_e32 v14, 7, v5
	v_mov_b32_e32 v5, v161
	s_lshl_b32 s0, s0, 5
	v_lshl_add_u64 v[0:1], s[18:19], 0, v[160:161]
	v_lshl_add_u64 v[2:3], s[20:21], 0, v[160:161]
	v_or_b32_e32 v26, s1, v19
	v_lshl_add_u64 v[4:5], s[50:51], 0, v[4:5]
	s_add_i32 s80, s27, s0
	v_lshlrev_b32_e32 v6, 1, v6
	v_lshlrev_b32_e32 v8, 1, v8
	v_lshlrev_b32_e32 v10, 1, v10
	v_lshlrev_b32_e32 v12, 1, v12
	v_lshlrev_b32_e32 v14, 1, v14
	v_add_u32_e32 v27, 0x400, v20
	v_add_u32_e32 v28, 0x800, v20
	v_add_u32_e32 v29, 0xc00, v20
	v_add_u32_e32 v30, 0x1000, v20
	v_add_u32_e32 v31, 0x1400, v20
	v_add_u32_e32 v32, 0x1800, v20
	v_add_u32_e32 v33, 0x1c00, v20
	s_cmpk_lt_i32 s78, 0x600
	s_cbranch_scc1 .Lp1_cv_p0
	s_add_i32 s81, s78, 0xfffffa00
	s_movk_i32 s98, 0x200
	s_movk_i32 s100, 0x8ff
	s_branch .Lp1_cv_go
.Lp1_cv_p0:
	s_add_i32 s81, s78, 0x900
	s_movk_i32 s98, 0x800
	s_movk_i32 s100, 0xeff
.Lp1_cv_go:
	s_lshl_b32 s80, s81, 5
	s_lshl_b32 s99, s98, 5
	s_branch .LBB0_37

; __device__ __forceinline__ void phase1(LAS unsigned char* lds, const Params& P) {
;     ...
;     for (int it = gw; it < I_IN + I_OUT + I_LRU; it += NGW) {
.LBB0_36:
	s_add_i32 s81, s81, s98
	s_add_i32 s80, s80, s99
	s_cmp_gt_i32 s81, s100
	s_cbranch_scc1 .LBB0_52
